# v82 + SSD hand-off acquire: one buffer_inv per block (thread 0 before the workgroup barrier) instead of one per wave
# speedup vs baseline: 1.0459x; 1.0061x over previous
; DI unsigned flag_ld(unsigned* f) { return __hip_atomic_load(f, __ATOMIC_RELAXED, __HIP_MEMORY_SCOPE_AGENT); }
; template <int PROBE>
; PH void ssd_prompt_item(const Params& p, int layer, int b, int e, int seg) {
;     ...
;   if (seg > 0) {
;     if (tid == 0) {
;       unsigned sp = 0;
;       while (flag_ld(SFLAG + seg - 1) == 0u) { __builtin_amdgcn_s_sleep(2); if (++sp > (1u << 22)) break; }
;     }
;     __syncthreads();
;     __builtin_amdgcn_fence(__ATOMIC_ACQUIRE, "agent");
;     asm volatile("s_waitcnt vmcnt(0)" ::: "memory");
;     const float* hin = SEND + (size_t)(seg - 1) * 8192 + eoff;
.LBB0_499:
	s_cbranch_execz .Lacq1_skip
	s_waitcnt vmcnt(0)
	buffer_inv sc1
	s_waitcnt vmcnt(0)
	s_nop 0
	s_nop 0
	s_nop 0
	s_nop 0
	s_nop 0
	s_nop 0
	s_nop 0
	s_nop 0
	s_nop 0
	s_nop 0
	s_nop 0
	s_nop 0
	s_nop 0
	s_nop 0
	s_nop 0
	s_nop 0
	s_nop 0
	s_nop 0
	s_nop 0
	s_nop 0
	s_nop 0
	s_nop 0
	s_nop 0
	s_nop 0
	s_nop 0
	s_nop 0
	s_nop 0
	s_nop 0
	s_nop 0
	s_nop 0
	s_nop 0
	s_nop 0
	s_nop 0
	s_nop 0
	s_nop 0
	s_nop 0
	s_nop 0
	s_nop 0
	s_nop 0
	s_nop 0
	s_nop 0
	s_nop 0
	s_nop 0
	s_nop 0
	s_nop 0
	s_nop 0
	s_nop 0
	s_nop 0
	s_nop 0
	s_nop 0
	s_nop 0
	s_nop 0
	s_nop 0
	s_nop 0
	s_nop 0
	s_nop 0
	s_nop 0
	s_nop 0
	s_nop 0
.Lacq1_skip:
	s_or_b64 exec, exec, s[6:7]
	s_add_i32 s2, s86, -1
	s_lshl_b64 s[0:1], s[2:3], 15
	s_add_u32 s0, s36, s0
	s_addc_u32 s1, s37, s1
	v_lshlrev_b64 v[0:1], 2, v[64:65]
	s_barrier
	s_waitcnt vmcnt(0)
	s_nop 0
	s_nop 0
	s_waitcnt vmcnt(0)
	v_lshl_add_u64 v[28:29], s[0:1], 0, v[0:1]
	v_lshl_add_u64 v[0:1], s[36:37], 0, v[0:1]
	s_lshl_b64 s[0:1], s[86:87], 15
	v_lshl_add_u64 v[64:65], v[0:1], 0, s[0:1]
	global_load_dwordx4 v[0:3], v[28:29], off
	v_exp_f32_e32 v66, v66
	v_cndmask_b32_e64 v4, 0, 1, s[48:49]
	v_cmp_ne_u32_e64 s[0:1], 1, v4
	s_andn2_b64 vcc, exec, s[48:49]
	v_mov_b32_e32 v67, v66
	s_cbranch_vccz .LBB0_612
	global_load_dwordx4 v[4:7], v[28:29], off offset:64
	s_and_b64 vcc, exec, s[0:1]
	s_cbranch_vccz .LBB0_613
